# v10 + G3 (GLU) GEMM: swapped MFMA operands and hand-written silu*up epilogue with 8-byte stores
# baseline (speedup 1.0000x reference)
; #define STAGE8(P, BASE, br, kt) do { const bf16_t* _g = (BASE) + (size_t)(br) * K + (kt) * 64; \
;     _Pragma("unroll") for (int _i = 0; _i < 2; ++_i) \
;       __builtin_amdgcn_global_load_lds((glb_u32*)(_g + goff0 + _i * 64 * K), (lds_u32*)((char*)(P) + tid * 16 + _i * 8192), 16, 0, 0); } while (0)
; #define LDA8(dst, b, h) _Pragma("unroll") for (int m = 0; m < 4; ++m) _Pragma("unroll") for (int k = 0; k < 2; ++k) \
;     dst[m][k] = *reinterpret_cast<const bf16x8*>((const char*)SA8(b, h) + lds_byte(wr * 64 + m * 16 + fr, k * 32 + fq * 8))
; #define LDB8(dst, b, h) _Pragma("unroll") for (int n = 0; n < 2; ++n) _Pragma("unroll") for (int k = 0; k < 2; ++k) \
;     dst[n][k] = *reinterpret_cast<const bf16x8*>((const char*)SB8(b, h) + lds_byte(wc * 32 + n * 16 + fr, k * 32 + fq * 8))
; #define MMA8(ai, bj, Af, Bf) do { __builtin_amdgcn_s_setprio(3); \
;     _Pragma("unroll") for (int m = 0; m < 4; ++m) _Pragma("unroll") for (int n = 0; n < 2; ++n) _Pragma("unroll") for (int k = 0; k < 2; ++k) \
;       acc[ai][bj][m][n] = __builtin_amdgcn_mfma_f32_16x16x32_bf16(Af[m][k], Bf[n][k], acc[ai][bj][m][n], 0, 0, 0); \
;     __builtin_amdgcn_s_setprio(0); } while (0)
; #define WAIT_L8(n) asm volatile("s_waitcnt lgkmcnt(" #n ")" ::: "memory")
; #define BAR8 __builtin_amdgcn_s_barrier()
; #define SCHED8 __builtin_amdgcn_sched_barrier(0)
; template <int EPI>
; __device__ __forceinline__ void gemm_tile8p(const bf16_t* __restrict__ Ag, const bf16_t* __restrict__ Bg, int K, int nt, int brow, int bcol,
;                                             char* smem, void* outp, int ldo, int nvalid, int rowoff, int rowlim) {
;     ...
;   for (int t = 0; t < nt - 2; t += 2) {
;     LDB8(B0, 0, 0); SCHED8; LDA8(At, 0, 0); STAGE8(SA8(1, 1), Ag, brow + HALF, t + 1);
;     WAIT_L8(8); BAR8; WAIT_L8(0); MMA8(0, 0, At, B0); BAR8; SCHED8;
;     LDB8(B1, 0, 1); STAGE8(SB8(0, 0), Bg, bcol, t + 2);
;     BAR8; WAIT_L8(0); MMA8(0, 1, At, B1); BAR8;
;     LDA8(At, 0, 1); STAGE8(SA8(0, 0), Ag, brow, t + 2);
;     BAR8; WAIT_L8(0); MMA8(1, 0, At, B0); BAR8; SCHED8;
.LBB0_174:
	ds_read_b128 v[164:167], v161
	ds_read_b128 v[168:171], v161 offset:1024
	ds_read_b128 v[172:175], v161 offset:2048
	ds_read_b128 v[176:179], v161 offset:3072
	v_add_u32_e32 v162, 0xc000, v137
	v_lshl_add_u64 v[230:231], s[40:41], 0, v[130:131]
	v_readfirstlane_b32 s3, v162
	v_add_u32_e32 v163, 0xe000, v137
	v_lshl_add_u64 v[232:233], v[230:231], 0, s[4:5]
	s_mov_b32 m0, s3
	v_readfirstlane_b32 s3, v163
	ds_read_b128 v[180:183], v141
	ds_read_b128 v[184:187], v141 offset:1024
	ds_read_b128 v[188:191], v140
	ds_read_b128 v[192:195], v140 offset:1024
	ds_read_b128 v[196:199], v139
	ds_read_b128 v[200:203], v139 offset:1024
	ds_read_b128 v[204:207], v138
	ds_read_b128 v[208:211], v138 offset:1024
	global_load_lds_dwordx4 v[232:233], off
	v_lshl_add_u64 v[232:233], v[230:231], 0, s[8:9]
	s_mov_b32 m0, s3
	s_nop 0
	global_load_lds_dwordx4 v[232:233], off
	s_waitcnt lgkmcnt(8)
	s_barrier
	s_waitcnt lgkmcnt(0)
	s_setprio 3
	s_waitcnt lgkmcnt(0)
	v_mfma_f32_16x16x32_bf16 v[124:127], v[164:167], v[180:183], v[124:127]
	v_mfma_f32_16x16x32_bf16 v[120:123], v[172:175], v[180:183], v[120:123]
	v_mfma_f32_16x16x32_bf16 v[116:119], v[164:167], v[188:191], v[116:119]
	v_mfma_f32_16x16x32_bf16 v[112:115], v[172:175], v[188:191], v[112:115]
	v_mfma_f32_16x16x32_bf16 v[108:111], v[164:167], v[196:199], v[108:111]
	v_mfma_f32_16x16x32_bf16 v[104:107], v[172:175], v[196:199], v[104:107]
	v_mfma_f32_16x16x32_bf16 v[100:103], v[164:167], v[204:207], v[100:103]
	v_mfma_f32_16x16x32_bf16 v[96:99], v[172:175], v[204:207], v[96:99]
	v_mfma_f32_16x16x32_bf16 v[124:127], v[168:171], v[184:187], v[124:127]
	v_mfma_f32_16x16x32_bf16 v[120:123], v[176:179], v[184:187], v[120:123]
	v_mfma_f32_16x16x32_bf16 v[116:119], v[168:171], v[192:195], v[116:119]
	v_mfma_f32_16x16x32_bf16 v[112:115], v[176:179], v[192:195], v[112:115]
	v_mfma_f32_16x16x32_bf16 v[108:111], v[168:171], v[200:203], v[108:111]
	v_mfma_f32_16x16x32_bf16 v[104:107], v[176:179], v[200:203], v[104:107]
	v_mfma_f32_16x16x32_bf16 v[100:103], v[168:171], v[208:211], v[100:103]
	v_mfma_f32_16x16x32_bf16 v[96:99], v[176:179], v[208:211], v[96:99]
	s_setprio 0
	s_barrier
	v_lshl_add_u64 v[248:249], s[42:43], 0, v[130:131]
	v_readfirstlane_b32 s3, v142
	v_lshl_add_u64 v[250:251], v[248:249], 0, s[12:13]
	s_mov_b32 m0, s3
	v_readfirstlane_b32 s3, v143
	ds_read_b128 v[232:235], v157
	ds_read_b128 v[236:239], v157 offset:1024
	ds_read_b128 v[240:243], v157 offset:2048
	ds_read_b128 v[244:247], v157 offset:3072
	global_load_lds_dwordx4 v[250:251], off
	v_lshl_add_u64 v[250:251], v[248:249], 0, s[28:29]
	s_mov_b32 m0, s3
	s_nop 0
	global_load_lds_dwordx4 v[250:251], off
	s_barrier
	s_waitcnt lgkmcnt(0)
	s_setprio 3
	s_waitcnt lgkmcnt(0)
	v_mfma_f32_16x16x32_bf16 v[92:95], v[232:235], v[180:183], v[92:95]
	v_mfma_f32_16x16x32_bf16 v[88:91], v[240:243], v[180:183], v[88:91]
	v_mfma_f32_16x16x32_bf16 v[84:87], v[232:235], v[188:191], v[84:87]
	v_mfma_f32_16x16x32_bf16 v[80:83], v[240:243], v[188:191], v[80:83]
	v_mfma_f32_16x16x32_bf16 v[76:79], v[232:235], v[196:199], v[76:79]
	v_mfma_f32_16x16x32_bf16 v[72:75], v[240:243], v[196:199], v[72:75]
	v_mfma_f32_16x16x32_bf16 v[68:71], v[232:235], v[204:207], v[68:71]
	v_mfma_f32_16x16x32_bf16 v[64:67], v[240:243], v[204:207], v[64:67]
	v_mfma_f32_16x16x32_bf16 v[92:95], v[236:239], v[184:187], v[92:95]
	v_mfma_f32_16x16x32_bf16 v[88:91], v[244:247], v[184:187], v[88:91]
	v_mfma_f32_16x16x32_bf16 v[84:87], v[236:239], v[192:195], v[84:87]
	v_mfma_f32_16x16x32_bf16 v[80:83], v[244:247], v[192:195], v[80:83]
	v_mfma_f32_16x16x32_bf16 v[76:79], v[236:239], v[200:203], v[76:79]
	v_mfma_f32_16x16x32_bf16 v[72:75], v[244:247], v[200:203], v[72:75]
	v_mfma_f32_16x16x32_bf16 v[68:71], v[236:239], v[208:211], v[68:71]
	v_mfma_f32_16x16x32_bf16 v[64:67], v[244:247], v[208:211], v[64:67]
	s_setprio 0
	v_readfirstlane_b32 s3, v137
	v_lshl_add_u64 v[250:251], v[230:231], 0, s[30:31]
	s_mov_b32 m0, s3
	v_readfirstlane_b32 s3, v145
	s_barrier
	ds_read_b128 v[180:183], v141 offset:16384
	ds_read_b128 v[184:187], v141 offset:17408
	ds_read_b128 v[188:191], v140 offset:16384
	ds_read_b128 v[192:195], v140 offset:17408
	ds_read_b128 v[196:199], v139 offset:16384
	ds_read_b128 v[200:203], v139 offset:17408
	ds_read_b128 v[204:207], v138 offset:16384
	ds_read_b128 v[208:211], v138 offset:17408
	global_load_lds_dwordx4 v[250:251], off
	v_lshl_add_u64 v[250:251], v[230:231], 0, s[34:35]
	s_mov_b32 m0, s3
	s_nop 0
	global_load_lds_dwordx4 v[250:251], off
	s_barrier
	s_waitcnt lgkmcnt(0)
	s_setprio 3
	s_waitcnt lgkmcnt(0)
	v_mfma_f32_16x16x32_bf16 v[60:63], v[164:167], v[180:183], v[60:63]
	v_mfma_f32_16x16x32_bf16 v[56:59], v[172:175], v[180:183], v[56:59]
	v_mfma_f32_16x16x32_bf16 v[52:55], v[164:167], v[188:191], v[52:55]
	v_mfma_f32_16x16x32_bf16 v[48:51], v[172:175], v[188:191], v[48:51]
	v_mfma_f32_16x16x32_bf16 v[44:47], v[164:167], v[196:199], v[44:47]
	v_mfma_f32_16x16x32_bf16 v[40:43], v[172:175], v[196:199], v[40:43]
	v_mfma_f32_16x16x32_bf16 v[36:39], v[164:167], v[204:207], v[36:39]
	v_mfma_f32_16x16x32_bf16 v[32:35], v[172:175], v[204:207], v[32:35]
	v_mfma_f32_16x16x32_bf16 v[60:63], v[168:171], v[184:187], v[60:63]
	v_mfma_f32_16x16x32_bf16 v[56:59], v[176:179], v[184:187], v[56:59]
	v_mfma_f32_16x16x32_bf16 v[52:55], v[168:171], v[192:195], v[52:55]
	v_mfma_f32_16x16x32_bf16 v[48:51], v[176:179], v[192:195], v[48:51]
	v_mfma_f32_16x16x32_bf16 v[44:47], v[168:171], v[200:203], v[44:47]
	v_mfma_f32_16x16x32_bf16 v[40:43], v[176:179], v[200:203], v[40:43]
	v_mfma_f32_16x16x32_bf16 v[36:39], v[168:171], v[208:211], v[36:39]
	v_mfma_f32_16x16x32_bf16 v[32:35], v[176:179], v[208:211], v[32:35]
	s_setprio 0
	s_barrier
; #define STAGE8(P, BASE, br, kt) do { const bf16_t* _g = (BASE) + (size_t)(br) * K + (kt) * 64; \
;     _Pragma("unroll") for (int _i = 0; _i < 2; ++_i) \
;       __builtin_amdgcn_global_load_lds((glb_u32*)(_g + goff0 + _i * 64 * K), (lds_u32*)((char*)(P) + tid * 16 + _i * 8192), 16, 0, 0); } while (0)
; #define LDA8(dst, b, h) _Pragma("unroll") for (int m = 0; m < 4; ++m) _Pragma("unroll") for (int k = 0; k < 2; ++k) \
;     dst[m][k] = *reinterpret_cast<const bf16x8*>((const char*)SA8(b, h) + lds_byte(wr * 64 + m * 16 + fr, k * 32 + fq * 8))
; #define LDB8(dst, b, h) _Pragma("unroll") for (int n = 0; n < 2; ++n) _Pragma("unroll") for (int k = 0; k < 2; ++k) \
;     dst[n][k] = *reinterpret_cast<const bf16x8*>((const char*)SB8(b, h) + lds_byte(wc * 32 + n * 16 + fr, k * 32 + fq * 8))
; #define MMA8(ai, bj, Af, Bf) do { __builtin_amdgcn_s_setprio(3); \
;     _Pragma("unroll") for (int m = 0; m < 4; ++m) _Pragma("unroll") for (int n = 0; n < 2; ++n) _Pragma("unroll") for (int k = 0; k < 2; ++k) \
;       acc[ai][bj][m][n] = __builtin_amdgcn_mfma_f32_16x16x32_bf16(Af[m][k], Bf[n][k], acc[ai][bj][m][n], 0, 0, 0); \
;     __builtin_amdgcn_s_setprio(0); } while (0)
; #define WAIT_V8(n) asm volatile("s_waitcnt vmcnt(" #n ")" ::: "memory")
; #define WAIT_L8(n) asm volatile("s_waitcnt lgkmcnt(" #n ")" ::: "memory")
; #define BAR8 __builtin_amdgcn_s_barrier()
; #define SCHED8 __builtin_amdgcn_sched_barrier(0)
; template <int EPI>
; __device__ __forceinline__ void gemm_tile8p(const bf16_t* __restrict__ Ag, const bf16_t* __restrict__ Bg, int K, int nt, int brow, int bcol,
;                                             char* smem, void* outp, int ldo, int nvalid, int rowoff, int rowlim) {
;     ...
;     STAGE8(SB8(0, 1), Bg, bcol + HALF, t + 2);
;     WAIT_V8(6); BAR8; MMA8(1, 1, At, B1); BAR8;
;     LDB8(B0, 1, 0); SCHED8; LDA8(At, 1, 0); STAGE8(SA8(0, 1), Ag, brow + HALF, t + 2);
;     WAIT_L8(8); BAR8; WAIT_L8(0); MMA8(0, 0, At, B0); BAR8; SCHED8;
;     LDB8(B1, 1, 1); STAGE8(SB8(1, 0), Bg, bcol, t + 3);
;     BAR8; WAIT_L8(0); MMA8(0, 1, At, B1); BAR8;
;     LDA8(At, 1, 1); STAGE8(SA8(1, 0), Ag, brow, t + 3);
	v_readfirstlane_b32 s3, v147
	v_lshl_add_u64 v[164:165], v[248:249], 0, s[44:45]
	s_mov_b32 m0, s3
	v_readfirstlane_b32 s3, v148
	global_load_lds_dwordx4 v[164:165], off
	v_lshl_add_u64 v[164:165], v[248:249], 0, s[64:65]
	s_mov_b32 m0, s3
	s_nop 0
	global_load_lds_dwordx4 v[164:165], off
	s_waitcnt vmcnt(6)
	s_barrier
	s_setprio 3
	v_mfma_f32_16x16x32_bf16 v[28:31], v[232:235], v[180:183], v[28:31]
	v_mfma_f32_16x16x32_bf16 v[24:27], v[240:243], v[180:183], v[24:27]
	v_mfma_f32_16x16x32_bf16 v[20:23], v[232:235], v[188:191], v[20:23]
	v_mfma_f32_16x16x32_bf16 v[16:19], v[240:243], v[188:191], v[16:19]
	v_mfma_f32_16x16x32_bf16 v[12:15], v[232:235], v[196:199], v[12:15]
	v_mfma_f32_16x16x32_bf16 v[8:11], v[240:243], v[196:199], v[8:11]
	v_mfma_f32_16x16x32_bf16 v[4:7], v[232:235], v[204:207], v[4:7]
	v_mfma_f32_16x16x32_bf16 v[0:3], v[240:243], v[204:207], v[0:3]
	v_mfma_f32_16x16x32_bf16 v[28:31], v[236:239], v[184:187], v[28:31]
	v_mfma_f32_16x16x32_bf16 v[24:27], v[244:247], v[184:187], v[24:27]
	v_mfma_f32_16x16x32_bf16 v[20:23], v[236:239], v[192:195], v[20:23]
	v_mfma_f32_16x16x32_bf16 v[16:19], v[244:247], v[192:195], v[16:19]
	v_mfma_f32_16x16x32_bf16 v[12:15], v[236:239], v[200:203], v[12:15]
	v_mfma_f32_16x16x32_bf16 v[8:11], v[244:247], v[200:203], v[8:11]
	v_mfma_f32_16x16x32_bf16 v[4:7], v[236:239], v[208:211], v[4:7]
	v_mfma_f32_16x16x32_bf16 v[0:3], v[244:247], v[208:211], v[0:3]
	s_setprio 0
	s_barrier
	ds_read_b128 v[164:167], v146
	ds_read_b128 v[168:171], v146 offset:1024
	ds_read_b128 v[172:175], v146 offset:2048
	ds_read_b128 v[176:179], v146 offset:3072
	v_readfirstlane_b32 s3, v152
	v_lshl_add_u64 v[232:233], v[230:231], 0, s[86:87]
	s_mov_b32 m0, s3
	v_readfirstlane_b32 s3, v153
	ds_read_b128 v[180:183], v141 offset:32768
	ds_read_b128 v[184:187], v141 offset:33792
	ds_read_b128 v[188:191], v140 offset:32768
	ds_read_b128 v[192:195], v140 offset:33792
	ds_read_b128 v[196:199], v139 offset:32768
	ds_read_b128 v[200:203], v139 offset:33792
	ds_read_b128 v[204:207], v138 offset:32768
	ds_read_b128 v[208:211], v138 offset:33792
	global_load_lds_dwordx4 v[232:233], off
	v_lshl_add_u64 v[232:233], v[230:231], 0, s[90:91]
	s_mov_b32 m0, s3
	s_nop 0
	global_load_lds_dwordx4 v[232:233], off
	s_waitcnt lgkmcnt(8)
	s_barrier
	s_waitcnt lgkmcnt(0)
	s_setprio 3
	s_waitcnt lgkmcnt(0)
	v_mfma_f32_16x16x32_bf16 v[124:127], v[164:167], v[180:183], v[124:127]
	v_mfma_f32_16x16x32_bf16 v[120:123], v[172:175], v[180:183], v[120:123]
	v_mfma_f32_16x16x32_bf16 v[116:119], v[164:167], v[188:191], v[116:119]
	v_mfma_f32_16x16x32_bf16 v[112:115], v[172:175], v[188:191], v[112:115]
	v_mfma_f32_16x16x32_bf16 v[108:111], v[164:167], v[196:199], v[108:111]
	v_mfma_f32_16x16x32_bf16 v[104:107], v[172:175], v[196:199], v[104:107]
	v_mfma_f32_16x16x32_bf16 v[100:103], v[164:167], v[204:207], v[100:103]
	v_mfma_f32_16x16x32_bf16 v[96:99], v[172:175], v[204:207], v[96:99]
	v_mfma_f32_16x16x32_bf16 v[124:127], v[168:171], v[184:187], v[124:127]
	v_mfma_f32_16x16x32_bf16 v[120:123], v[176:179], v[184:187], v[120:123]
	v_mfma_f32_16x16x32_bf16 v[116:119], v[168:171], v[192:195], v[116:119]
	v_mfma_f32_16x16x32_bf16 v[112:115], v[176:179], v[192:195], v[112:115]
	v_mfma_f32_16x16x32_bf16 v[108:111], v[168:171], v[200:203], v[108:111]
	v_mfma_f32_16x16x32_bf16 v[104:107], v[176:179], v[200:203], v[104:107]
	v_mfma_f32_16x16x32_bf16 v[100:103], v[168:171], v[208:211], v[100:103]
	v_mfma_f32_16x16x32_bf16 v[96:99], v[176:179], v[208:211], v[96:99]
	s_setprio 0
	s_barrier
	v_readfirstlane_b32 s3, v154
	v_lshl_add_u64 v[250:251], v[248:249], 0, s[94:95]
	s_mov_b32 m0, s3
	v_readfirstlane_b32 s3, v155
	ds_read_b128 v[232:235], v144
	ds_read_b128 v[236:239], v144 offset:1024
	ds_read_b128 v[240:243], v144 offset:2048
	ds_read_b128 v[244:247], v144 offset:3072
	global_load_lds_dwordx4 v[250:251], off
	v_lshl_add_u64 v[250:251], v[248:249], 0, s[96:97]
	s_mov_b32 m0, s3
	s_nop 0
	global_load_lds_dwordx4 v[250:251], off
	s_barrier
	s_waitcnt lgkmcnt(0)
	s_setprio 3
	s_waitcnt lgkmcnt(0)
	v_mfma_f32_16x16x32_bf16 v[92:95], v[232:235], v[180:183], v[92:95]
	v_mfma_f32_16x16x32_bf16 v[88:91], v[240:243], v[180:183], v[88:91]
	v_mfma_f32_16x16x32_bf16 v[84:87], v[232:235], v[188:191], v[84:87]
	v_mfma_f32_16x16x32_bf16 v[80:83], v[240:243], v[188:191], v[80:83]
	v_mfma_f32_16x16x32_bf16 v[76:79], v[232:235], v[196:199], v[76:79]
	v_mfma_f32_16x16x32_bf16 v[72:75], v[240:243], v[196:199], v[72:75]
	v_mfma_f32_16x16x32_bf16 v[68:71], v[232:235], v[204:207], v[68:71]
	v_mfma_f32_16x16x32_bf16 v[64:67], v[240:243], v[204:207], v[64:67]
	v_mfma_f32_16x16x32_bf16 v[92:95], v[236:239], v[184:187], v[92:95]
	v_mfma_f32_16x16x32_bf16 v[88:91], v[244:247], v[184:187], v[88:91]
	v_mfma_f32_16x16x32_bf16 v[84:87], v[236:239], v[192:195], v[84:87]
	v_mfma_f32_16x16x32_bf16 v[80:83], v[244:247], v[192:195], v[80:83]
	v_mfma_f32_16x16x32_bf16 v[76:79], v[236:239], v[200:203], v[76:79]
	v_mfma_f32_16x16x32_bf16 v[72:75], v[244:247], v[200:203], v[72:75]
	v_mfma_f32_16x16x32_bf16 v[68:71], v[236:239], v[208:211], v[68:71]
	v_mfma_f32_16x16x32_bf16 v[64:67], v[244:247], v[208:211], v[64:67]
	s_setprio 0
	v_readfirstlane_b32 s3, v156
	v_lshl_add_u64 v[250:251], v[230:231], 0, vcc
	s_mov_b32 m0, s3
	v_readfirstlane_b32 s3, v158
	s_barrier
	ds_read_b128 v[180:183], v141 offset:49152
	ds_read_b128 v[184:187], v141 offset:50176
	ds_read_b128 v[188:191], v140 offset:49152
	ds_read_b128 v[192:195], v140 offset:50176
	ds_read_b128 v[196:199], v139 offset:49152
	ds_read_b128 v[200:203], v139 offset:50176
	ds_read_b128 v[204:207], v138 offset:49152
	ds_read_b128 v[208:211], v138 offset:50176
	global_load_lds_dwordx4 v[250:251], off
	v_lshl_add_u64 v[230:231], v[230:231], 0, s[74:75]
	s_mov_b32 m0, s3
	s_nop 0
	global_load_lds_dwordx4 v[230:231], off
	s_barrier
; #define STAGE8(P, BASE, br, kt) do { const bf16_t* _g = (BASE) + (size_t)(br) * K + (kt) * 64; \
;     _Pragma("unroll") for (int _i = 0; _i < 2; ++_i) \
;       __builtin_amdgcn_global_load_lds((glb_u32*)(_g + goff0 + _i * 64 * K), (lds_u32*)((char*)(P) + tid * 16 + _i * 8192), 16, 0, 0); } while (0)
; #define LDA8(dst, b, h) _Pragma("unroll") for (int m = 0; m < 4; ++m) _Pragma("unroll") for (int k = 0; k < 2; ++k) \
;     dst[m][k] = *reinterpret_cast<const bf16x8*>((const char*)SA8(b, h) + lds_byte(wr * 64 + m * 16 + fr, k * 32 + fq * 8))
; #define LDB8(dst, b, h) _Pragma("unroll") for (int n = 0; n < 2; ++n) _Pragma("unroll") for (int k = 0; k < 2; ++k) \
;     dst[n][k] = *reinterpret_cast<const bf16x8*>((const char*)SB8(b, h) + lds_byte(wc * 32 + n * 16 + fr, k * 32 + fq * 8))
; #define MMA8(ai, bj, Af, Bf) do { __builtin_amdgcn_s_setprio(3); \
;     _Pragma("unroll") for (int m = 0; m < 4; ++m) _Pragma("unroll") for (int n = 0; n < 2; ++n) _Pragma("unroll") for (int k = 0; k < 2; ++k) \
;       acc[ai][bj][m][n] = __builtin_amdgcn_mfma_f32_16x16x32_bf16(Af[m][k], Bf[n][k], acc[ai][bj][m][n], 0, 0, 0); \
;     __builtin_amdgcn_s_setprio(0); } while (0)
; #define WAIT_V8(n) asm volatile("s_waitcnt vmcnt(" #n ")" ::: "memory")
; #define WAIT_L8(n) asm volatile("s_waitcnt lgkmcnt(" #n ")" ::: "memory")
; #define BAR8 __builtin_amdgcn_s_barrier()
; #define SCHED8 __builtin_amdgcn_sched_barrier(0)
; template <int EPI>
; __device__ __forceinline__ void gemm_tile8p(const bf16_t* __restrict__ Ag, const bf16_t* __restrict__ Bg, int K, int nt, int brow, int bcol,
;                                             char* smem, void* outp, int ldo, int nvalid, int rowoff, int rowlim) {
;     ...
;     BAR8; WAIT_L8(0); MMA8(1, 0, At, B0); BAR8; SCHED8;
;     STAGE8(SB8(1, 1), Bg, bcol + HALF, t + 3);
;     WAIT_V8(6); BAR8; MMA8(1, 1, At, B1); BAR8;
;   }
;   { LDB8(B0, 0, 0); LDA8(At, 0, 0); STAGE8(SA8(1, 1), Ag, brow + HALF, nt - 1);
;     BAR8; WAIT_L8(0); MMA8(0, 0, At, B0); BAR8;
;     LDB8(B1, 0, 1); BAR8; WAIT_L8(0); MMA8(0, 1, At, B1); BAR8;
	s_waitcnt lgkmcnt(0)
	s_setprio 3
	s_waitcnt lgkmcnt(0)
	v_mfma_f32_16x16x32_bf16 v[60:63], v[164:167], v[180:183], v[60:63]
	v_mfma_f32_16x16x32_bf16 v[56:59], v[172:175], v[180:183], v[56:59]
	v_mfma_f32_16x16x32_bf16 v[52:55], v[164:167], v[188:191], v[52:55]
	v_mfma_f32_16x16x32_bf16 v[48:51], v[172:175], v[188:191], v[48:51]
	v_mfma_f32_16x16x32_bf16 v[44:47], v[164:167], v[196:199], v[44:47]
	v_mfma_f32_16x16x32_bf16 v[40:43], v[172:175], v[196:199], v[40:43]
	v_mfma_f32_16x16x32_bf16 v[36:39], v[164:167], v[204:207], v[36:39]
	v_mfma_f32_16x16x32_bf16 v[32:35], v[172:175], v[204:207], v[32:35]
	v_mfma_f32_16x16x32_bf16 v[60:63], v[168:171], v[184:187], v[60:63]
	v_mfma_f32_16x16x32_bf16 v[56:59], v[176:179], v[184:187], v[56:59]
	v_mfma_f32_16x16x32_bf16 v[52:55], v[168:171], v[192:195], v[52:55]
	v_mfma_f32_16x16x32_bf16 v[48:51], v[176:179], v[192:195], v[48:51]
	v_mfma_f32_16x16x32_bf16 v[44:47], v[168:171], v[200:203], v[44:47]
	v_mfma_f32_16x16x32_bf16 v[40:43], v[176:179], v[200:203], v[40:43]
	v_mfma_f32_16x16x32_bf16 v[36:39], v[168:171], v[208:211], v[36:39]
	v_mfma_f32_16x16x32_bf16 v[32:35], v[176:179], v[208:211], v[32:35]
	s_setprio 0
	s_barrier
	v_readfirstlane_b32 s3, v159
	v_lshl_add_u64 v[164:165], v[248:249], 0, s[82:83]
	s_mov_b32 m0, s3
	v_readfirstlane_b32 s3, v160
	global_load_lds_dwordx4 v[164:165], off
	v_lshl_add_u64 v[164:165], v[248:249], 0, s[92:93]
	s_mov_b32 m0, s3
	s_nop 0
	global_load_lds_dwordx4 v[164:165], off
	s_waitcnt vmcnt(6)
	s_barrier
	s_setprio 3
	v_mfma_f32_16x16x32_bf16 v[28:31], v[232:235], v[180:183], v[28:31]
	v_mfma_f32_16x16x32_bf16 v[24:27], v[240:243], v[180:183], v[24:27]
	v_mfma_f32_16x16x32_bf16 v[20:23], v[232:235], v[188:191], v[20:23]
	v_mfma_f32_16x16x32_bf16 v[16:19], v[240:243], v[188:191], v[16:19]
	v_mfma_f32_16x16x32_bf16 v[12:15], v[232:235], v[196:199], v[12:15]
	v_mfma_f32_16x16x32_bf16 v[8:11], v[240:243], v[196:199], v[8:11]
	v_mfma_f32_16x16x32_bf16 v[4:7], v[232:235], v[204:207], v[4:7]
	v_mfma_f32_16x16x32_bf16 v[0:3], v[240:243], v[204:207], v[0:3]
	v_mfma_f32_16x16x32_bf16 v[28:31], v[236:239], v[184:187], v[28:31]
	v_mfma_f32_16x16x32_bf16 v[24:27], v[244:247], v[184:187], v[24:27]
	v_mfma_f32_16x16x32_bf16 v[20:23], v[236:239], v[192:195], v[20:23]
	v_mfma_f32_16x16x32_bf16 v[16:19], v[244:247], v[192:195], v[16:19]
	v_mfma_f32_16x16x32_bf16 v[12:15], v[236:239], v[200:203], v[12:15]
	v_mfma_f32_16x16x32_bf16 v[8:11], v[244:247], v[200:203], v[8:11]
	v_mfma_f32_16x16x32_bf16 v[4:7], v[236:239], v[208:211], v[4:7]
	v_mfma_f32_16x16x32_bf16 v[0:3], v[244:247], v[208:211], v[0:3]
	s_setprio 0
	s_add_i32 s2, s2, 2
	s_add_u32 s40, s40, 0x100
	s_addc_u32 s41, s41, 0
	s_add_u32 s42, s42, 0x100
	s_addc_u32 s43, s43, 0
	s_cmp_lt_u32 s2, 12
	s_barrier
	s_cbranch_scc1 .LBB0_174
	s_mov_b64 s[2:3], 0x780
	v_lshl_add_u64 v[130:131], v[128:129], 0, s[2:3]
	v_readfirstlane_b32 s2, v162
	s_mov_b32 m0, s2
	s_mov_b64 s[2:3], 0x20780
	v_lshl_add_u64 v[128:129], v[128:129], 0, s[2:3]
	v_readfirstlane_b32 s2, v163
	ds_read_b128 v[152:155], v161
	ds_read_b128 v[164:167], v161 offset:1024
	ds_read_b128 v[168:171], v161 offset:2048
	ds_read_b128 v[158:161], v161 offset:3072
	ds_read_b128 v[172:175], v141
	ds_read_b128 v[176:179], v141 offset:1024
	ds_read_b128 v[180:183], v140
	ds_read_b128 v[184:187], v140 offset:1024
	ds_read_b128 v[188:191], v139
	ds_read_b128 v[192:195], v139 offset:1024
	ds_read_b128 v[196:199], v138
	ds_read_b128 v[200:203], v138 offset:1024
	global_load_lds_dwordx4 v[130:131], off
	s_mov_b32 m0, s2
	s_nop 0
	global_load_lds_dwordx4 v[128:129], off
	s_barrier
	s_waitcnt lgkmcnt(0)
	s_setprio 3
	s_waitcnt lgkmcnt(0)
	v_mfma_f32_16x16x32_bf16 v[124:127], v[152:155], v[172:175], v[124:127]
	v_mfma_f32_16x16x32_bf16 v[116:119], v[152:155], v[180:183], v[116:119]
	v_mfma_f32_16x16x32_bf16 v[108:111], v[152:155], v[188:191], v[108:111]
	v_mfma_f32_16x16x32_bf16 v[100:103], v[152:155], v[196:199], v[100:103]
	v_mfma_f32_16x16x32_bf16 v[124:127], v[164:167], v[176:179], v[124:127]
	v_mfma_f32_16x16x32_bf16 v[120:123], v[168:171], v[172:175], v[120:123]
	v_mfma_f32_16x16x32_bf16 v[116:119], v[164:167], v[184:187], v[116:119]
	v_mfma_f32_16x16x32_bf16 v[112:115], v[168:171], v[180:183], v[112:115]
	v_mfma_f32_16x16x32_bf16 v[108:111], v[164:167], v[192:195], v[108:111]
	v_mfma_f32_16x16x32_bf16 v[104:107], v[168:171], v[188:191], v[104:107]
	v_mfma_f32_16x16x32_bf16 v[100:103], v[164:167], v[200:203], v[100:103]
	v_mfma_f32_16x16x32_bf16 v[96:99], v[168:171], v[196:199], v[96:99]
	v_mfma_f32_16x16x32_bf16 v[128:131], v[158:161], v[176:179], v[120:123]
	v_mfma_f32_16x16x32_bf16 v[204:207], v[158:161], v[184:187], v[112:115]
	v_mfma_f32_16x16x32_bf16 v[208:211], v[158:161], v[192:195], v[104:107]
	v_mfma_f32_16x16x32_bf16 v[232:235], v[158:161], v[200:203], v[96:99]
	s_setprio 0
	s_barrier
	s_nop 1
	ds_read_b128 v[96:99], v157
	ds_read_b128 v[104:107], v157 offset:1024
	ds_read_b128 v[112:115], v157 offset:2048
	ds_read_b128 v[120:123], v157 offset:3072
	s_barrier
	s_waitcnt lgkmcnt(0)
	s_setprio 3
	s_waitcnt lgkmcnt(0)
	v_mfma_f32_16x16x32_bf16 v[92:95], v[96:99], v[172:175], v[92:95]
	v_mfma_f32_16x16x32_bf16 v[84:87], v[96:99], v[180:183], v[84:87]
	v_mfma_f32_16x16x32_bf16 v[76:79], v[96:99], v[188:191], v[76:79]
	v_mfma_f32_16x16x32_bf16 v[68:71], v[96:99], v[196:199], v[68:71]
	v_mfma_f32_16x16x32_bf16 v[92:95], v[104:107], v[176:179], v[92:95]
	v_mfma_f32_16x16x32_bf16 v[88:91], v[112:115], v[172:175], v[88:91]
	v_mfma_f32_16x16x32_bf16 v[84:87], v[104:107], v[184:187], v[84:87]
	v_mfma_f32_16x16x32_bf16 v[80:83], v[112:115], v[180:183], v[80:83]
	v_mfma_f32_16x16x32_bf16 v[76:79], v[104:107], v[192:195], v[76:79]
	v_mfma_f32_16x16x32_bf16 v[72:75], v[112:115], v[188:191], v[72:75]
	v_mfma_f32_16x16x32_bf16 v[68:71], v[104:107], v[200:203], v[68:71]
	v_mfma_f32_16x16x32_bf16 v[64:67], v[112:115], v[196:199], v[64:67]
	v_mfma_f32_16x16x32_bf16 v[172:175], v[120:123], v[176:179], v[88:91]
	v_mfma_f32_16x16x32_bf16 v[176:179], v[120:123], v[184:187], v[80:83]
	v_mfma_f32_16x16x32_bf16 v[180:183], v[120:123], v[192:195], v[72:75]
	v_mfma_f32_16x16x32_bf16 v[184:187], v[120:123], v[200:203], v[64:67]
	s_setprio 0
	s_barrier
; #define LDA8(dst, b, h) _Pragma("unroll") for (int m = 0; m < 4; ++m) _Pragma("unroll") for (int k = 0; k < 2; ++k) \
;     dst[m][k] = *reinterpret_cast<const bf16x8*>((const char*)SA8(b, h) + lds_byte(wr * 64 + m * 16 + fr, k * 32 + fq * 8))
; #define LDB8(dst, b, h) _Pragma("unroll") for (int n = 0; n < 2; ++n) _Pragma("unroll") for (int k = 0; k < 2; ++k) \
;     dst[n][k] = *reinterpret_cast<const bf16x8*>((const char*)SB8(b, h) + lds_byte(wc * 32 + n * 16 + fr, k * 32 + fq * 8))
; #define MMA8(ai, bj, Af, Bf) do { __builtin_amdgcn_s_setprio(3); \
;     _Pragma("unroll") for (int m = 0; m < 4; ++m) _Pragma("unroll") for (int n = 0; n < 2; ++n) _Pragma("unroll") for (int k = 0; k < 2; ++k) \
;       acc[ai][bj][m][n] = __builtin_amdgcn_mfma_f32_16x16x32_bf16(Af[m][k], Bf[n][k], acc[ai][bj][m][n], 0, 0, 0); \
;     __builtin_amdgcn_s_setprio(0); } while (0)
; #define WAIT_V8(n) asm volatile("s_waitcnt vmcnt(" #n ")" ::: "memory")
; #define WAIT_L8(n) asm volatile("s_waitcnt lgkmcnt(" #n ")" ::: "memory")
; #define BAR8 __builtin_amdgcn_s_barrier()
; template <int EPI>
; __device__ __forceinline__ void gemm_tile8p(const bf16_t* __restrict__ Ag, const bf16_t* __restrict__ Bg, int K, int nt, int brow, int bcol,
;                                             char* smem, void* outp, int ldo, int nvalid, int rowoff, int rowlim) {
;     ...
;     LDA8(At, 0, 1); WAIT_V8(4); BAR8; WAIT_L8(0); MMA8(1, 0, At, B0); MMA8(1, 1, At, B1); BAR8; }
;   { LDB8(B0, 1, 0); LDA8(At, 1, 0); WAIT_V8(2); BAR8; WAIT_L8(0); MMA8(0, 0, At, B0); BAR8;
;     LDB8(B1, 1, 1); WAIT_V8(0); BAR8; WAIT_L8(0); MMA8(0, 1, At, B1); BAR8;
	s_nop 1
	ds_read_b128 v[64:67], v141 offset:16384
	ds_read_b128 v[72:75], v141 offset:17408
	ds_read_b128 v[80:83], v140 offset:16384
	ds_read_b128 v[88:91], v140 offset:17408
	ds_read_b128 v[188:191], v139 offset:16384
	ds_read_b128 v[192:195], v139 offset:17408
	ds_read_b128 v[196:199], v138 offset:16384
	ds_read_b128 v[200:203], v138 offset:17408
	s_waitcnt vmcnt(4)
	s_barrier
	s_waitcnt lgkmcnt(0)
	s_setprio 3
	s_waitcnt lgkmcnt(0)
	v_mfma_f32_16x16x32_bf16 v[60:63], v[152:155], v[64:67], v[60:63]
	v_mfma_f32_16x16x32_bf16 v[52:55], v[152:155], v[80:83], v[52:55]
	v_mfma_f32_16x16x32_bf16 v[44:47], v[152:155], v[188:191], v[44:47]
	v_mfma_f32_16x16x32_bf16 v[36:39], v[152:155], v[196:199], v[36:39]
	v_mfma_f32_16x16x32_bf16 v[60:63], v[164:167], v[72:75], v[60:63]
	v_mfma_f32_16x16x32_bf16 v[56:59], v[168:171], v[64:67], v[56:59]
	v_mfma_f32_16x16x32_bf16 v[52:55], v[164:167], v[88:91], v[52:55]
	v_mfma_f32_16x16x32_bf16 v[48:51], v[168:171], v[80:83], v[48:51]
	v_mfma_f32_16x16x32_bf16 v[44:47], v[164:167], v[192:195], v[44:47]
	v_mfma_f32_16x16x32_bf16 v[40:43], v[168:171], v[188:191], v[40:43]
	v_mfma_f32_16x16x32_bf16 v[36:39], v[164:167], v[200:203], v[36:39]
	v_mfma_f32_16x16x32_bf16 v[32:35], v[168:171], v[196:199], v[32:35]
	v_mfma_f32_16x16x32_bf16 v[236:239], v[158:161], v[72:75], v[56:59]
	v_mfma_f32_16x16x32_bf16 v[240:243], v[158:161], v[88:91], v[48:51]
	v_mfma_f32_16x16x32_bf16 v[244:247], v[158:161], v[192:195], v[40:43]
	v_mfma_f32_16x16x32_bf16 v[152:155], v[158:161], v[200:203], v[32:35]
	s_setprio 0
	s_setprio 3
	v_mfma_f32_16x16x32_bf16 v[28:31], v[96:99], v[64:67], v[28:31]
	v_mfma_f32_16x16x32_bf16 v[20:23], v[96:99], v[80:83], v[20:23]
	v_mfma_f32_16x16x32_bf16 v[12:15], v[96:99], v[188:191], v[12:15]
	v_mfma_f32_16x16x32_bf16 v[4:7], v[96:99], v[196:199], v[4:7]
	v_mfma_f32_16x16x32_bf16 v[28:31], v[104:107], v[72:75], v[28:31]
	v_mfma_f32_16x16x32_bf16 v[24:27], v[112:115], v[64:67], v[24:27]
	v_mfma_f32_16x16x32_bf16 v[20:23], v[104:107], v[88:91], v[20:23]
	v_mfma_f32_16x16x32_bf16 v[16:19], v[112:115], v[80:83], v[16:19]
	v_mfma_f32_16x16x32_bf16 v[12:15], v[104:107], v[192:195], v[12:15]
	v_mfma_f32_16x16x32_bf16 v[8:11], v[112:115], v[188:191], v[8:11]
	v_mfma_f32_16x16x32_bf16 v[4:7], v[104:107], v[200:203], v[4:7]
	v_mfma_f32_16x16x32_bf16 v[0:3], v[112:115], v[196:199], v[0:3]
	v_mfma_f32_16x16x32_bf16 v[156:159], v[120:123], v[72:75], v[24:27]
	v_mfma_f32_16x16x32_bf16 v[160:163], v[120:123], v[88:91], v[16:19]
	v_mfma_f32_16x16x32_bf16 v[164:167], v[120:123], v[192:195], v[8:11]
	v_mfma_f32_16x16x32_bf16 v[168:171], v[120:123], v[200:203], v[0:3]
	s_setprio 0
	s_barrier
	s_nop 1
	ds_read_b128 v[0:3], v146
	ds_read_b128 v[8:11], v146 offset:1024
	ds_read_b128 v[188:191], v146 offset:2048
	ds_read_b128 v[192:195], v146 offset:3072
	ds_read_b128 v[16:19], v141 offset:32768
	ds_read_b128 v[24:27], v141 offset:33792
	ds_read_b128 v[32:35], v140 offset:32768
	ds_read_b128 v[40:43], v140 offset:33792
	ds_read_b128 v[48:51], v139 offset:32768
	ds_read_b128 v[56:59], v139 offset:33792
	ds_read_b128 v[196:199], v138 offset:32768
	ds_read_b128 v[200:203], v138 offset:33792
	s_waitcnt vmcnt(2)
	s_barrier
	s_waitcnt lgkmcnt(0)
	s_setprio 3
	s_waitcnt lgkmcnt(0)
	v_mfma_f32_16x16x32_bf16 v[64:67], v[0:3], v[16:19], v[124:127]
	v_mfma_f32_16x16x32_bf16 v[120:123], v[8:11], v[24:27], v[64:67]
	v_mfma_f32_16x16x32_bf16 v[64:67], v[188:191], v[16:19], v[128:131]
	v_mfma_f32_16x16x32_bf16 v[112:115], v[192:195], v[24:27], v[64:67]
	v_mfma_f32_16x16x32_bf16 v[64:67], v[0:3], v[32:35], v[116:119]
	v_mfma_f32_16x16x32_bf16 v[104:107], v[8:11], v[40:43], v[64:67]
	v_mfma_f32_16x16x32_bf16 v[64:67], v[188:191], v[32:35], v[204:207]
	v_mfma_f32_16x16x32_bf16 v[96:99], v[192:195], v[40:43], v[64:67]
	v_mfma_f32_16x16x32_bf16 v[64:67], v[0:3], v[48:51], v[108:111]
	v_mfma_f32_16x16x32_bf16 v[88:91], v[8:11], v[56:59], v[64:67]
	v_mfma_f32_16x16x32_bf16 v[64:67], v[188:191], v[48:51], v[208:211]
	v_mfma_f32_16x16x32_bf16 v[80:83], v[192:195], v[56:59], v[64:67]
	v_mfma_f32_16x16x32_bf16 v[64:67], v[0:3], v[196:199], v[100:103]
	v_mfma_f32_16x16x32_bf16 v[72:75], v[8:11], v[200:203], v[64:67]
	v_mfma_f32_16x16x32_bf16 v[64:67], v[188:191], v[196:199], v[232:235]
	v_mfma_f32_16x16x32_bf16 v[64:67], v[192:195], v[200:203], v[64:67]
	s_setprio 0
	s_barrier
	ds_read_b128 v[128:131], v144
	ds_read_b128 v[204:207], v144 offset:1024
	ds_read_b128 v[208:211], v144 offset:2048
	ds_read_b128 v[142:145], v144 offset:3072
	s_waitcnt vmcnt(0)
	s_barrier
	s_waitcnt lgkmcnt(0)
	s_setprio 3
	s_waitcnt lgkmcnt(0)
	v_mfma_f32_16x16x32_bf16 v[92:95], v[128:131], v[16:19], v[92:95]
	v_mfma_f32_16x16x32_bf16 v[16:19], v[208:211], v[16:19], v[172:175]
	v_mfma_f32_16x16x32_bf16 v[116:119], v[142:145], v[24:27], v[16:19]
	v_mfma_f32_16x16x32_bf16 v[16:19], v[128:131], v[32:35], v[84:87]
	v_mfma_f32_16x16x32_bf16 v[108:111], v[204:207], v[40:43], v[16:19]
	v_mfma_f32_16x16x32_bf16 v[16:19], v[208:211], v[32:35], v[176:179]
	v_mfma_f32_16x16x32_bf16 v[100:103], v[142:145], v[40:43], v[16:19]
	v_mfma_f32_16x16x32_bf16 v[16:19], v[128:131], v[48:51], v[76:79]
	v_mfma_f32_16x16x32_bf16 v[124:127], v[204:207], v[24:27], v[92:95]
	v_mfma_f32_16x16x32_bf16 v[92:95], v[204:207], v[56:59], v[16:19]
	v_mfma_f32_16x16x32_bf16 v[16:19], v[208:211], v[48:51], v[180:183]
	v_mfma_f32_16x16x32_bf16 v[84:87], v[142:145], v[56:59], v[16:19]
	v_mfma_f32_16x16x32_bf16 v[16:19], v[128:131], v[196:199], v[68:71]
	v_mfma_f32_16x16x32_bf16 v[76:79], v[204:207], v[200:203], v[16:19]
	v_mfma_f32_16x16x32_bf16 v[16:19], v[208:211], v[196:199], v[184:187]
	v_mfma_f32_16x16x32_bf16 v[68:71], v[142:145], v[200:203], v[16:19]
	s_setprio 0
	s_barrier
; __device__ __forceinline__ bf16_t f2bf(float f) { return (bf16_t)(pack2(f, 0.f) & 0xffffu); }
; __device__ __forceinline__ float siluf_(float x) { return x * __builtin_amdgcn_rcpf(1.f + __expf(-x)); }
; #define LDA8(dst, b, h) _Pragma("unroll") for (int m = 0; m < 4; ++m) _Pragma("unroll") for (int k = 0; k < 2; ++k) \
;     dst[m][k] = *reinterpret_cast<const bf16x8*>((const char*)SA8(b, h) + lds_byte(wr * 64 + m * 16 + fr, k * 32 + fq * 8))
; #define MMA8(ai, bj, Af, Bf) do { __builtin_amdgcn_s_setprio(3); \
;     _Pragma("unroll") for (int m = 0; m < 4; ++m) _Pragma("unroll") for (int n = 0; n < 2; ++n) _Pragma("unroll") for (int k = 0; k < 2; ++k) \
;       acc[ai][bj][m][n] = __builtin_amdgcn_mfma_f32_16x16x32_bf16(Af[m][k], Bf[n][k], acc[ai][bj][m][n], 0, 0, 0); \
;     __builtin_amdgcn_s_setprio(0); } while (0)
; #define WAIT_L8(n) asm volatile("s_waitcnt lgkmcnt(" #n ")" ::: "memory")
; #define BAR8 __builtin_amdgcn_s_barrier()
; template <int EPI>
; __device__ __forceinline__ void gemm_tile8p(const bf16_t* __restrict__ Ag, const bf16_t* __restrict__ Bg, int K, int nt, int brow, int bcol,
;                                             char* smem, void* outp, int ldo, int nvalid, int rowoff, int rowlim) {
;     ...
;     LDA8(At, 1, 1); BAR8; WAIT_L8(0); MMA8(1, 0, At, B0); MMA8(1, 1, At, B1); BAR8; }
;   if (wr == 0) BAR8;
; #pragma unroll
;   for (int ai = 0; ai < 2; ++ai)
; #pragma unroll
;     for (int m = 0; m < 4; ++m)
; #pragma unroll
;       for (int j = 0; j < 4; ++j) {
;         const int rl = ai * HALF + wr * 64 + m * 16 + fq * 4 + j;
;         const size_t orow = (size_t)(rowoff + rl) * ldo;
;         if (EPI == EPI_GLU) {
; #pragma unroll
;           for (int n = 0; n < 2; ++n) {
;             const int col = (bcol >> 8) * 128 + wc * 32 + n * 16 + fr;
;             const float g = acc[ai][0][m][n][j], u = acc[ai][1][m][n][j];
;             if (rl < rowlim) ((bf16_t*)outp)[orow + col] = f2bf(siluf_(g) * u);
;           }
	ds_read_b128 v[172:175], v141 offset:49152
	ds_read_b128 v[176:179], v141 offset:50176
	ds_read_b128 v[180:183], v140 offset:49152
	ds_read_b128 v[184:187], v140 offset:50176
	ds_read_b128 v[196:199], v139 offset:49152
	ds_read_b128 v[200:203], v139 offset:50176
	ds_read_b128 v[232:235], v138 offset:49152
	ds_read_b128 v[138:141], v138 offset:50176
	s_barrier
	s_waitcnt lgkmcnt(0)
	s_setprio 3
	s_waitcnt lgkmcnt(0)
	v_mfma_f32_16x16x32_bf16 v[16:19], v[0:3], v[172:175], v[60:63]
	v_mfma_f32_16x16x32_bf16 v[56:59], v[8:11], v[176:179], v[16:19]
	v_mfma_f32_16x16x32_bf16 v[16:19], v[188:191], v[172:175], v[236:239]
	v_mfma_f32_16x16x32_bf16 v[48:51], v[192:195], v[176:179], v[16:19]
	v_mfma_f32_16x16x32_bf16 v[16:19], v[0:3], v[180:183], v[52:55]
	v_mfma_f32_16x16x32_bf16 v[40:43], v[8:11], v[184:187], v[16:19]
	v_mfma_f32_16x16x32_bf16 v[16:19], v[188:191], v[180:183], v[240:243]
	v_mfma_f32_16x16x32_bf16 v[32:35], v[192:195], v[184:187], v[16:19]
	v_mfma_f32_16x16x32_bf16 v[16:19], v[0:3], v[196:199], v[44:47]
	v_mfma_f32_16x16x32_bf16 v[0:3], v[0:3], v[232:235], v[36:39]
	v_mfma_f32_16x16x32_bf16 v[24:27], v[8:11], v[200:203], v[16:19]
	v_mfma_f32_16x16x32_bf16 v[16:19], v[188:191], v[196:199], v[244:247]
	v_mfma_f32_16x16x32_bf16 v[8:11], v[8:11], v[138:141], v[0:3]
	v_mfma_f32_16x16x32_bf16 v[0:3], v[188:191], v[232:235], v[152:155]
	v_mfma_f32_16x16x32_bf16 v[16:19], v[192:195], v[200:203], v[16:19]
	v_mfma_f32_16x16x32_bf16 v[0:3], v[192:195], v[138:141], v[0:3]
	s_setprio 0
	s_setprio 3
	v_mfma_f32_16x16x32_bf16 v[28:31], v[128:131], v[172:175], v[28:31]
	v_mfma_f32_16x16x32_bf16 v[60:63], v[204:207], v[176:179], v[28:31]
	v_mfma_f32_16x16x32_bf16 v[28:31], v[208:211], v[172:175], v[156:159]
	v_mfma_f32_16x16x32_bf16 v[20:23], v[128:131], v[180:183], v[20:23]
	v_mfma_f32_16x16x32_bf16 v[12:15], v[128:131], v[196:199], v[12:15]
	v_mfma_f32_16x16x32_bf16 v[52:55], v[142:145], v[176:179], v[28:31]
	v_mfma_f32_16x16x32_bf16 v[44:47], v[204:207], v[184:187], v[20:23]
	v_mfma_f32_16x16x32_bf16 v[20:23], v[208:211], v[180:183], v[160:163]
	v_mfma_f32_16x16x32_bf16 v[28:31], v[204:207], v[200:203], v[12:15]
	v_mfma_f32_16x16x32_bf16 v[12:15], v[208:211], v[196:199], v[164:167]
	v_mfma_f32_16x16x32_bf16 v[4:7], v[128:131], v[232:235], v[4:7]
	v_mfma_f32_16x16x32_bf16 v[36:39], v[142:145], v[184:187], v[20:23]
	v_mfma_f32_16x16x32_bf16 v[20:23], v[142:145], v[200:203], v[12:15]
	v_mfma_f32_16x16x32_bf16 v[12:15], v[204:207], v[138:141], v[4:7]
	v_mfma_f32_16x16x32_bf16 v[4:7], v[208:211], v[232:235], v[168:171]
	v_mfma_f32_16x16x32_bf16 v[4:7], v[142:145], v[138:141], v[4:7]
	s_setprio 0
	v_cmp_gt_u32_e32 vcc, s58, v132
	s_barrier
	s_and_saveexec_b64 s[2:3], vcc
	s_cbranch_execz .LBB0_177
	s_barrier
.LBB0_177:
	s_or_b64 exec, exec, s[2:3]
	v_readlane_b32 s8, v253, 63
	v_readlane_b32 s9, v254, 0
	s_lshl_b32 s2, s11, 7
	s_sub_i32 s4, 0x4080, s38
	s_load_dwordx2 s[92:93], s[8:9], 0x128
	v_or_b32_e32 v160, v136, v134
	v_lshlrev_b32_e32 v162, 5, v133
	v_lshl_or_b32 v162, v135, 2, v162
	v_or_b32_e32 v162, s2, v162
	v_mov_b32_e32 v163, 0
	v_lshl_add_u64 v[164:165], v[162:163], 1, s[68:69]
	s_mov_b32 s12, 0xbfb8aa3b
	v_mov_b32_e32 v166, v160
	v_cmp_gt_i32_e64 s[2:3], s4, v166
	v_add_u32_e32 v166, s38, v166
	v_mad_u64_u32 v[168:169], vcc, v166, s1, v[164:165]
	v_mul_f32_e32 v170, s12, v120
	v_mul_f32_e32 v171, s12, v121
	v_mul_f32_e32 v172, s12, v122
	v_mul_f32_e32 v173, s12, v123
	v_mul_f32_e32 v174, s12, v112
	v_mul_f32_e32 v175, s12, v113
	v_mul_f32_e32 v176, s12, v114
	v_mul_f32_e32 v177, s12, v115
	v_exp_f32_e32 v170, v170
	v_exp_f32_e32 v171, v171
	v_exp_f32_e32 v172, v172
	v_exp_f32_e32 v173, v173
	v_exp_f32_e32 v174, v174
	v_exp_f32_e32 v175, v175
	v_exp_f32_e32 v176, v176
	v_exp_f32_e32 v177, v177
	v_add_f32_e32 v170, 1.0, v170
	v_add_f32_e32 v171, 1.0, v171
	v_add_f32_e32 v172, 1.0, v172
	v_add_f32_e32 v173, 1.0, v173
	v_add_f32_e32 v174, 1.0, v174
	v_add_f32_e32 v175, 1.0, v175
	v_add_f32_e32 v176, 1.0, v176
	v_add_f32_e32 v177, 1.0, v177
	v_rcp_f32_e32 v170, v170
	v_rcp_f32_e32 v171, v171
	v_rcp_f32_e32 v172, v172
	v_rcp_f32_e32 v173, v173
	v_rcp_f32_e32 v174, v174
	v_rcp_f32_e32 v175, v175
	v_rcp_f32_e32 v176, v176
	v_rcp_f32_e32 v177, v177
	v_mul_f32_e32 v170, v120, v170
	v_mul_f32_e32 v171, v121, v171
	v_mul_f32_e32 v172, v122, v172
	v_mul_f32_e32 v173, v123, v173
	v_mul_f32_e32 v174, v112, v174
	v_mul_f32_e32 v175, v113, v175
	v_mul_f32_e32 v176, v114, v176
	v_mul_f32_e32 v177, v115, v177
	v_mul_f32_e32 v170, v170, v124
	v_mul_f32_e32 v171, v171, v125
	v_mul_f32_e32 v172, v172, v126
	v_mul_f32_e32 v173, v173, v127
	v_mul_f32_e32 v174, v174, v116
	v_mul_f32_e32 v175, v175, v117
	v_mul_f32_e32 v176, v176, v118
	v_mul_f32_e32 v177, v177, v119
	v_cvt_pk_bf16_f32 v170, v170, v171
	v_cvt_pk_bf16_f32 v171, v172, v173
	v_cvt_pk_bf16_f32 v174, v174, v175
	v_cvt_pk_bf16_f32 v175, v176, v177
	s_mov_b64 exec, s[2:3]
	global_store_dwordx2 v[168:169], v[170:171], off
	global_store_dwordx2 v[168:169], v[174:175], off offset:32
	s_mov_b64 exec, -1
	v_add_u32_e32 v166, 16, v160
	v_cmp_gt_i32_e64 s[2:3], s4, v166
	v_add_u32_e32 v166, s38, v166
	v_mad_u64_u32 v[168:169], vcc, v166, s1, v[164:165]
	v_mul_f32_e32 v170, s12, v104
	v_mul_f32_e32 v171, s12, v105
	v_mul_f32_e32 v172, s12, v106
	v_mul_f32_e32 v173, s12, v107
	v_mul_f32_e32 v174, s12, v96
	v_mul_f32_e32 v175, s12, v97
	v_mul_f32_e32 v176, s12, v98
	v_mul_f32_e32 v177, s12, v99
	v_exp_f32_e32 v170, v170
	v_exp_f32_e32 v171, v171
	v_exp_f32_e32 v172, v172
	v_exp_f32_e32 v173, v173
	v_exp_f32_e32 v174, v174
	v_exp_f32_e32 v175, v175
	v_exp_f32_e32 v176, v176
	v_exp_f32_e32 v177, v177
; __device__ __forceinline__ bf16_t f2bf(float f) { return (bf16_t)(pack2(f, 0.f) & 0xffffu); }
; __device__ __forceinline__ float siluf_(float x) { return x * __builtin_amdgcn_rcpf(1.f + __expf(-x)); }
; template <int EPI>
; __device__ __forceinline__ void gemm_tile8p(const bf16_t* __restrict__ Ag, const bf16_t* __restrict__ Bg, int K, int nt, int brow, int bcol,
;                                             char* smem, void* outp, int ldo, int nvalid, int rowoff, int rowlim) {
;     ...
; #pragma unroll
;   for (int ai = 0; ai < 2; ++ai)
; #pragma unroll
;     for (int m = 0; m < 4; ++m)
; #pragma unroll
;       for (int j = 0; j < 4; ++j) {
;         const int rl = ai * HALF + wr * 64 + m * 16 + fq * 4 + j;
;         const size_t orow = (size_t)(rowoff + rl) * ldo;
;         if (EPI == EPI_GLU) {
; #pragma unroll
;           for (int n = 0; n < 2; ++n) {
;             const int col = (bcol >> 8) * 128 + wc * 32 + n * 16 + fr;
;             const float g = acc[ai][0][m][n][j], u = acc[ai][1][m][n][j];
;             if (rl < rowlim) ((bf16_t*)outp)[orow + col] = f2bf(siluf_(g) * u);
;           }
	v_add_f32_e32 v170, 1.0, v170
	v_add_f32_e32 v171, 1.0, v171
	v_add_f32_e32 v172, 1.0, v172
	v_add_f32_e32 v173, 1.0, v173
	v_add_f32_e32 v174, 1.0, v174
	v_add_f32_e32 v175, 1.0, v175
	v_add_f32_e32 v176, 1.0, v176
	v_add_f32_e32 v177, 1.0, v177
	v_rcp_f32_e32 v170, v170
	v_rcp_f32_e32 v171, v171
	v_rcp_f32_e32 v172, v172
	v_rcp_f32_e32 v173, v173
	v_rcp_f32_e32 v174, v174
	v_rcp_f32_e32 v175, v175
	v_rcp_f32_e32 v176, v176
	v_rcp_f32_e32 v177, v177
	v_mul_f32_e32 v170, v104, v170
	v_mul_f32_e32 v171, v105, v171
	v_mul_f32_e32 v172, v106, v172
	v_mul_f32_e32 v173, v107, v173
	v_mul_f32_e32 v174, v96, v174
	v_mul_f32_e32 v175, v97, v175
	v_mul_f32_e32 v176, v98, v176
	v_mul_f32_e32 v177, v99, v177
	v_mul_f32_e32 v170, v170, v108
	v_mul_f32_e32 v171, v171, v109
	v_mul_f32_e32 v172, v172, v110
	v_mul_f32_e32 v173, v173, v111
	v_mul_f32_e32 v174, v174, v100
	v_mul_f32_e32 v175, v175, v101
	v_mul_f32_e32 v176, v176, v102
	v_mul_f32_e32 v177, v177, v103
	v_cvt_pk_bf16_f32 v170, v170, v171
	v_cvt_pk_bf16_f32 v171, v172, v173
	v_cvt_pk_bf16_f32 v174, v174, v175
	v_cvt_pk_bf16_f32 v175, v176, v177
	s_mov_b64 exec, s[2:3]
	global_store_dwordx2 v[168:169], v[170:171], off
	global_store_dwordx2 v[168:169], v[174:175], off offset:32
	s_mov_b64 exec, -1
	v_add_u32_e32 v166, 32, v160
	v_cmp_gt_i32_e64 s[2:3], s4, v166
	v_add_u32_e32 v166, s38, v166
	v_mad_u64_u32 v[168:169], vcc, v166, s1, v[164:165]
	v_mul_f32_e32 v170, s12, v88
	v_mul_f32_e32 v171, s12, v89
	v_mul_f32_e32 v172, s12, v90
	v_mul_f32_e32 v173, s12, v91
	v_mul_f32_e32 v174, s12, v80
	v_mul_f32_e32 v175, s12, v81
	v_mul_f32_e32 v176, s12, v82
	v_mul_f32_e32 v177, s12, v83
	v_exp_f32_e32 v170, v170
	v_exp_f32_e32 v171, v171
	v_exp_f32_e32 v172, v172
	v_exp_f32_e32 v173, v173
	v_exp_f32_e32 v174, v174
	v_exp_f32_e32 v175, v175
	v_exp_f32_e32 v176, v176
	v_exp_f32_e32 v177, v177
	v_add_f32_e32 v170, 1.0, v170
	v_add_f32_e32 v171, 1.0, v171
	v_add_f32_e32 v172, 1.0, v172
	v_add_f32_e32 v173, 1.0, v173
	v_add_f32_e32 v174, 1.0, v174
	v_add_f32_e32 v175, 1.0, v175
	v_add_f32_e32 v176, 1.0, v176
	v_add_f32_e32 v177, 1.0, v177
	v_rcp_f32_e32 v170, v170
	v_rcp_f32_e32 v171, v171
	v_rcp_f32_e32 v172, v172
	v_rcp_f32_e32 v173, v173
	v_rcp_f32_e32 v174, v174
	v_rcp_f32_e32 v175, v175
	v_rcp_f32_e32 v176, v176
	v_rcp_f32_e32 v177, v177
	v_mul_f32_e32 v170, v88, v170
	v_mul_f32_e32 v171, v89, v171
	v_mul_f32_e32 v172, v90, v172
	v_mul_f32_e32 v173, v91, v173
	v_mul_f32_e32 v174, v80, v174
	v_mul_f32_e32 v175, v81, v175
	v_mul_f32_e32 v176, v82, v176
	v_mul_f32_e32 v177, v83, v177
	v_mul_f32_e32 v170, v170, v92
	v_mul_f32_e32 v171, v171, v93
	v_mul_f32_e32 v172, v172, v94
	v_mul_f32_e32 v173, v173, v95
	v_mul_f32_e32 v174, v174, v84
	v_mul_f32_e32 v175, v175, v85
	v_mul_f32_e32 v176, v176, v86
	v_mul_f32_e32 v177, v177, v87
	v_cvt_pk_bf16_f32 v170, v170, v171
	v_cvt_pk_bf16_f32 v171, v172, v173
	v_cvt_pk_bf16_f32 v174, v174, v175
	v_cvt_pk_bf16_f32 v175, v176, v177
	s_mov_b64 exec, s[2:3]
	global_store_dwordx2 v[168:169], v[170:171], off
	global_store_dwordx2 v[168:169], v[174:175], off offset:32
	s_mov_b64 exec, -1
	v_add_u32_e32 v166, 48, v160
	v_cmp_gt_i32_e64 s[2:3], s4, v166
	v_add_u32_e32 v166, s38, v166
	v_mad_u64_u32 v[168:169], vcc, v166, s1, v[164:165]
	v_mul_f32_e32 v170, s12, v72
	v_mul_f32_e32 v171, s12, v73
	v_mul_f32_e32 v172, s12, v74
	v_mul_f32_e32 v173, s12, v75
	v_mul_f32_e32 v174, s12, v64
	v_mul_f32_e32 v175, s12, v65
	v_mul_f32_e32 v176, s12, v66
	v_mul_f32_e32 v177, s12, v67
	v_exp_f32_e32 v170, v170
	v_exp_f32_e32 v171, v171
	v_exp_f32_e32 v172, v172
	v_exp_f32_e32 v173, v173
	v_exp_f32_e32 v174, v174
	v_exp_f32_e32 v175, v175
	v_exp_f32_e32 v176, v176
	v_exp_f32_e32 v177, v177
	v_add_f32_e32 v170, 1.0, v170
	v_add_f32_e32 v171, 1.0, v171
	v_add_f32_e32 v172, 1.0, v172
	v_add_f32_e32 v173, 1.0, v173
	v_add_f32_e32 v174, 1.0, v174
	v_add_f32_e32 v175, 1.0, v175
	v_add_f32_e32 v176, 1.0, v176
	v_add_f32_e32 v177, 1.0, v177
	v_rcp_f32_e32 v170, v170
	v_rcp_f32_e32 v171, v171
	v_rcp_f32_e32 v172, v172
	v_rcp_f32_e32 v173, v173
	v_rcp_f32_e32 v174, v174
	v_rcp_f32_e32 v175, v175
	v_rcp_f32_e32 v176, v176
	v_rcp_f32_e32 v177, v177
	v_mul_f32_e32 v170, v72, v170
	v_mul_f32_e32 v171, v73, v171
	v_mul_f32_e32 v172, v74, v172
	v_mul_f32_e32 v173, v75, v173
	v_mul_f32_e32 v174, v64, v174
	v_mul_f32_e32 v175, v65, v175
	v_mul_f32_e32 v176, v66, v176
	v_mul_f32_e32 v177, v67, v177
	v_mul_f32_e32 v170, v170, v76
	v_mul_f32_e32 v171, v171, v77
	v_mul_f32_e32 v172, v172, v78
	v_mul_f32_e32 v173, v173, v79
	v_mul_f32_e32 v174, v174, v68
	v_mul_f32_e32 v175, v175, v69
	v_mul_f32_e32 v176, v176, v70
	v_mul_f32_e32 v177, v177, v71
	v_cvt_pk_bf16_f32 v170, v170, v171
	v_cvt_pk_bf16_f32 v171, v172, v173
	v_cvt_pk_bf16_f32 v174, v174, v175
	v_cvt_pk_bf16_f32 v175, v176, v177
	s_mov_b64 exec, s[2:3]
	global_store_dwordx2 v[168:169], v[170:171], off
	global_store_dwordx2 v[168:169], v[174:175], off offset:32
	s_mov_b64 exec, -1
	v_add_u32_e32 v166, 128, v160
	v_cmp_gt_i32_e64 s[2:3], s4, v166
	v_add_u32_e32 v166, s38, v166
	v_mad_u64_u32 v[168:169], vcc, v166, s1, v[164:165]
	v_mul_f32_e32 v170, s12, v56
	v_mul_f32_e32 v171, s12, v57
	v_mul_f32_e32 v172, s12, v58
	v_mul_f32_e32 v173, s12, v59
	v_mul_f32_e32 v174, s12, v48
	v_mul_f32_e32 v175, s12, v49
	v_mul_f32_e32 v176, s12, v50
	v_mul_f32_e32 v177, s12, v51
	v_exp_f32_e32 v170, v170
	v_exp_f32_e32 v171, v171
	v_exp_f32_e32 v172, v172
	v_exp_f32_e32 v173, v173
	v_exp_f32_e32 v174, v174
	v_exp_f32_e32 v175, v175
	v_exp_f32_e32 v176, v176
	v_exp_f32_e32 v177, v177
	v_add_f32_e32 v170, 1.0, v170
	v_add_f32_e32 v171, 1.0, v171
	v_add_f32_e32 v172, 1.0, v172
; __device__ __forceinline__ bf16_t f2bf(float f) { return (bf16_t)(pack2(f, 0.f) & 0xffffu); }
; __device__ __forceinline__ float siluf_(float x) { return x * __builtin_amdgcn_rcpf(1.f + __expf(-x)); }
; template <int EPI>
; __device__ __forceinline__ void gemm_tile8p(const bf16_t* __restrict__ Ag, const bf16_t* __restrict__ Bg, int K, int nt, int brow, int bcol,
;                                             char* smem, void* outp, int ldo, int nvalid, int rowoff, int rowlim) {
;     ...
; #pragma unroll
;   for (int ai = 0; ai < 2; ++ai)
; #pragma unroll
;     for (int m = 0; m < 4; ++m)
; #pragma unroll
;       for (int j = 0; j < 4; ++j) {
;         const int rl = ai * HALF + wr * 64 + m * 16 + fq * 4 + j;
;         const size_t orow = (size_t)(rowoff + rl) * ldo;
;         if (EPI == EPI_GLU) {
; #pragma unroll
;           for (int n = 0; n < 2; ++n) {
;             const int col = (bcol >> 8) * 128 + wc * 32 + n * 16 + fr;
;             const float g = acc[ai][0][m][n][j], u = acc[ai][1][m][n][j];
;             if (rl < rowlim) ((bf16_t*)outp)[orow + col] = f2bf(siluf_(g) * u);
;           }
	v_add_f32_e32 v173, 1.0, v173
	v_add_f32_e32 v174, 1.0, v174
	v_add_f32_e32 v175, 1.0, v175
	v_add_f32_e32 v176, 1.0, v176
	v_add_f32_e32 v177, 1.0, v177
	v_rcp_f32_e32 v170, v170
	v_rcp_f32_e32 v171, v171
	v_rcp_f32_e32 v172, v172
	v_rcp_f32_e32 v173, v173
	v_rcp_f32_e32 v174, v174
	v_rcp_f32_e32 v175, v175
	v_rcp_f32_e32 v176, v176
	v_rcp_f32_e32 v177, v177
	v_mul_f32_e32 v170, v56, v170
	v_mul_f32_e32 v171, v57, v171
	v_mul_f32_e32 v172, v58, v172
	v_mul_f32_e32 v173, v59, v173
	v_mul_f32_e32 v174, v48, v174
	v_mul_f32_e32 v175, v49, v175
	v_mul_f32_e32 v176, v50, v176
	v_mul_f32_e32 v177, v51, v177
	v_mul_f32_e32 v170, v170, v60
	v_mul_f32_e32 v171, v171, v61
	v_mul_f32_e32 v172, v172, v62
	v_mul_f32_e32 v173, v173, v63
	v_mul_f32_e32 v174, v174, v52
	v_mul_f32_e32 v175, v175, v53
	v_mul_f32_e32 v176, v176, v54
	v_mul_f32_e32 v177, v177, v55
	v_cvt_pk_bf16_f32 v170, v170, v171
	v_cvt_pk_bf16_f32 v171, v172, v173
	v_cvt_pk_bf16_f32 v174, v174, v175
	v_cvt_pk_bf16_f32 v175, v176, v177
	s_mov_b64 exec, s[2:3]
	global_store_dwordx2 v[168:169], v[170:171], off
	global_store_dwordx2 v[168:169], v[174:175], off offset:32
	s_mov_b64 exec, -1
	v_add_u32_e32 v166, 144, v160
	v_cmp_gt_i32_e64 s[2:3], s4, v166
	v_add_u32_e32 v166, s38, v166
	v_mad_u64_u32 v[168:169], vcc, v166, s1, v[164:165]
	v_mul_f32_e32 v170, s12, v40
	v_mul_f32_e32 v171, s12, v41
	v_mul_f32_e32 v172, s12, v42
	v_mul_f32_e32 v173, s12, v43
	v_mul_f32_e32 v174, s12, v32
	v_mul_f32_e32 v175, s12, v33
	v_mul_f32_e32 v176, s12, v34
	v_mul_f32_e32 v177, s12, v35
	v_exp_f32_e32 v170, v170
	v_exp_f32_e32 v171, v171
	v_exp_f32_e32 v172, v172
	v_exp_f32_e32 v173, v173
	v_exp_f32_e32 v174, v174
	v_exp_f32_e32 v175, v175
	v_exp_f32_e32 v176, v176
	v_exp_f32_e32 v177, v177
	v_add_f32_e32 v170, 1.0, v170
	v_add_f32_e32 v171, 1.0, v171
	v_add_f32_e32 v172, 1.0, v172
	v_add_f32_e32 v173, 1.0, v173
	v_add_f32_e32 v174, 1.0, v174
	v_add_f32_e32 v175, 1.0, v175
	v_add_f32_e32 v176, 1.0, v176
	v_add_f32_e32 v177, 1.0, v177
	v_rcp_f32_e32 v170, v170
	v_rcp_f32_e32 v171, v171
	v_rcp_f32_e32 v172, v172
	v_rcp_f32_e32 v173, v173
	v_rcp_f32_e32 v174, v174
	v_rcp_f32_e32 v175, v175
	v_rcp_f32_e32 v176, v176
	v_rcp_f32_e32 v177, v177
	v_mul_f32_e32 v170, v40, v170
	v_mul_f32_e32 v171, v41, v171
	v_mul_f32_e32 v172, v42, v172
	v_mul_f32_e32 v173, v43, v173
	v_mul_f32_e32 v174, v32, v174
	v_mul_f32_e32 v175, v33, v175
	v_mul_f32_e32 v176, v34, v176
	v_mul_f32_e32 v177, v35, v177
	v_mul_f32_e32 v170, v170, v44
	v_mul_f32_e32 v171, v171, v45
	v_mul_f32_e32 v172, v172, v46
	v_mul_f32_e32 v173, v173, v47
	v_mul_f32_e32 v174, v174, v36
	v_mul_f32_e32 v175, v175, v37
	v_mul_f32_e32 v176, v176, v38
	v_mul_f32_e32 v177, v177, v39
	v_cvt_pk_bf16_f32 v170, v170, v171
	v_cvt_pk_bf16_f32 v171, v172, v173
	v_cvt_pk_bf16_f32 v174, v174, v175
	v_cvt_pk_bf16_f32 v175, v176, v177
	s_mov_b64 exec, s[2:3]
	global_store_dwordx2 v[168:169], v[170:171], off
	global_store_dwordx2 v[168:169], v[174:175], off offset:32
	s_mov_b64 exec, -1
	v_add_u32_e32 v166, 160, v160
	v_cmp_gt_i32_e64 s[2:3], s4, v166
	v_add_u32_e32 v166, s38, v166
	v_mad_u64_u32 v[168:169], vcc, v166, s1, v[164:165]
	v_mul_f32_e32 v170, s12, v24
	v_mul_f32_e32 v171, s12, v25
	v_mul_f32_e32 v172, s12, v26
	v_mul_f32_e32 v173, s12, v27
	v_mul_f32_e32 v174, s12, v16
	v_mul_f32_e32 v175, s12, v17
	v_mul_f32_e32 v176, s12, v18
	v_mul_f32_e32 v177, s12, v19
	v_exp_f32_e32 v170, v170
	v_exp_f32_e32 v171, v171
	v_exp_f32_e32 v172, v172
	v_exp_f32_e32 v173, v173
	v_exp_f32_e32 v174, v174
	v_exp_f32_e32 v175, v175
	v_exp_f32_e32 v176, v176
	v_exp_f32_e32 v177, v177
	v_add_f32_e32 v170, 1.0, v170
	v_add_f32_e32 v171, 1.0, v171
	v_add_f32_e32 v172, 1.0, v172
	v_add_f32_e32 v173, 1.0, v173
	v_add_f32_e32 v174, 1.0, v174
	v_add_f32_e32 v175, 1.0, v175
	v_add_f32_e32 v176, 1.0, v176
	v_add_f32_e32 v177, 1.0, v177
	v_rcp_f32_e32 v170, v170
	v_rcp_f32_e32 v171, v171
	v_rcp_f32_e32 v172, v172
	v_rcp_f32_e32 v173, v173
	v_rcp_f32_e32 v174, v174
	v_rcp_f32_e32 v175, v175
	v_rcp_f32_e32 v176, v176
	v_rcp_f32_e32 v177, v177
	v_mul_f32_e32 v170, v24, v170
	v_mul_f32_e32 v171, v25, v171
	v_mul_f32_e32 v172, v26, v172
	v_mul_f32_e32 v173, v27, v173
	v_mul_f32_e32 v174, v16, v174
	v_mul_f32_e32 v175, v17, v175
	v_mul_f32_e32 v176, v18, v176
	v_mul_f32_e32 v177, v19, v177
	v_mul_f32_e32 v170, v170, v28
	v_mul_f32_e32 v171, v171, v29
	v_mul_f32_e32 v172, v172, v30
	v_mul_f32_e32 v173, v173, v31
	v_mul_f32_e32 v174, v174, v20
	v_mul_f32_e32 v175, v175, v21
	v_mul_f32_e32 v176, v176, v22
	v_mul_f32_e32 v177, v177, v23
	v_cvt_pk_bf16_f32 v170, v170, v171
	v_cvt_pk_bf16_f32 v171, v172, v173
	v_cvt_pk_bf16_f32 v174, v174, v175
	v_cvt_pk_bf16_f32 v175, v176, v177
	s_mov_b64 exec, s[2:3]
	global_store_dwordx2 v[168:169], v[170:171], off
	global_store_dwordx2 v[168:169], v[174:175], off offset:32
	s_mov_b64 exec, -1
	v_add_u32_e32 v166, 176, v160
	v_cmp_gt_i32_e64 s[2:3], s4, v166
	v_add_u32_e32 v166, s38, v166
	v_mad_u64_u32 v[168:169], vcc, v166, s1, v[164:165]
	v_mul_f32_e32 v170, s12, v8
	v_mul_f32_e32 v171, s12, v9
	v_mul_f32_e32 v172, s12, v10
	v_mul_f32_e32 v173, s12, v11
	v_mul_f32_e32 v174, s12, v0
	v_mul_f32_e32 v175, s12, v1
	v_mul_f32_e32 v176, s12, v2
	v_mul_f32_e32 v177, s12, v3
	v_exp_f32_e32 v170, v170
	v_exp_f32_e32 v171, v171
	v_exp_f32_e32 v172, v172
	v_exp_f32_e32 v173, v173
	v_exp_f32_e32 v174, v174
	v_exp_f32_e32 v175, v175
	v_exp_f32_e32 v176, v176
	v_exp_f32_e32 v177, v177
	v_add_f32_e32 v170, 1.0, v170
	v_add_f32_e32 v171, 1.0, v171
	v_add_f32_e32 v172, 1.0, v172
	v_add_f32_e32 v173, 1.0, v173
	v_add_f32_e32 v174, 1.0, v174
	v_add_f32_e32 v175, 1.0, v175
	v_add_f32_e32 v176, 1.0, v176
	v_add_f32_e32 v177, 1.0, v177
	v_rcp_f32_e32 v170, v170
	v_rcp_f32_e32 v171, v171
	v_rcp_f32_e32 v172, v172
	v_rcp_f32_e32 v173, v173
	v_rcp_f32_e32 v174, v174
	v_rcp_f32_e32 v175, v175
	v_rcp_f32_e32 v176, v176
	v_rcp_f32_e32 v177, v177
	v_mul_f32_e32 v170, v8, v170
	v_mul_f32_e32 v171, v9, v171
	v_mul_f32_e32 v172, v10, v172
	v_mul_f32_e32 v173, v11, v173
	v_mul_f32_e32 v174, v0, v174
	v_mul_f32_e32 v175, v1, v175
	v_mul_f32_e32 v176, v2, v176
	v_mul_f32_e32 v177, v3, v177
	v_mul_f32_e32 v170, v170, v12
	v_mul_f32_e32 v171, v171, v13
	v_mul_f32_e32 v172, v172, v14
	v_mul_f32_e32 v173, v173, v15
	v_mul_f32_e32 v174, v174, v4
	v_mul_f32_e32 v175, v175, v5
	v_mul_f32_e32 v176, v176, v6
	v_mul_f32_e32 v177, v177, v7
	v_cvt_pk_bf16_f32 v170, v170, v171
	v_cvt_pk_bf16_f32 v171, v172, v173
	v_cvt_pk_bf16_f32 v174, v174, v175
	v_cvt_pk_bf16_f32 v175, v176, v177
	s_mov_b64 exec, s[2:3]
	global_store_dwordx2 v[168:169], v[170:171], off
	global_store_dwordx2 v[168:169], v[174:175], off offset:32
	s_mov_b64 exec, -1
	s_branch .LBB0_168
